# w28: w22 + non-temporal hint on the read-once loads of the gla_finalize row loop (keeps MIX resident for the out-projection GEMM)
# baseline (speedup 1.0000x reference)
; DI unsigned pk2(float lo, float hi) { f32x2 v = {lo, hi}; bf16x2_t b = __builtin_convertvector(v, bf16x2_t); return __builtin_bit_cast(unsigned, b); }
; DI float siluf_(float x) { return x * sigmoidf_(x); }
; DI f32x4 ldbf4(const bf16* p) { const u32x2 q = *(const u32x2*)p; return (f32x4){__builtin_bit_cast(float, q.x << 16), __builtin_bit_cast(float, q.x & 0xffff0000u), __builtin_bit_cast(float, q.y << 16), __builtin_bit_cast(float, q.y & 0xffff0000u)}; }
; DI void gla_finalize_phase(Frame& F) {
;     ...
;     for (int it0 = 4 * gw; it0 < MP * 4; it0 += 4 * NGW) {
;         const int row = it0 >> 2;
;         f32x4 o[4], gr[4];
; #pragma unroll
;         for (int h = 0; h < 4; ++h) { o[h] = *(const f32x4*)(F.ORAW + (size_t)row * 1024 + h * 256 + 4 * lane); gr[h] = ldbf4(F.G16 + (size_t)row * GLAW + 2048 + h * 256 + 4 * lane); }
; #pragma unroll
;         for (int h = 0; h < 4; ++h) {
;             const float ss = wave_sum((o[h][0] * o[h][0] + o[h][1] * o[h][1]) + (o[h][2] * o[h][2] + o[h][3] * o[h][3]));
;             const float rs = 1.f / sqrtf(ss * (1.f / 256.f) + LN_EPS);
;             u32x2 wv; wv.x = pk2(o[h][0] * rs * gn[0] * siluf_(gr[h][0]), o[h][1] * rs * gn[1] * siluf_(gr[h][1])); wv.y = pk2(o[h][2] * rs * gn[2] * siluf_(gr[h][2]), o[h][3] * rs * gn[3] * siluf_(gr[h][3]));
;             *(u32x2*)(F.MIX + (size_t)row * DM + h * 256 + 4 * lane) = wv; }
.LBB0_1727:
	s_ashr_i32 s0, s16, 2
	s_ashr_i32 s1, s0, 31
	s_mul_i32 s5, s0, 0x1800
	s_lshl_b64 s[2:3], s[0:1], 12
	s_mul_hi_i32 s4, s0, 0x1800
	v_lshl_add_u64 v[6:7], v[24:25], 0, s[2:3]
	s_add_u32 s0, s20, s5
	global_load_dwordx4 v[18:21], v[6:7], off nt
	global_load_dwordx4 v[14:17], v[6:7], off offset:1024 nt
	global_load_dwordx4 v[10:13], v[6:7], off offset:2048 nt
	s_waitcnt lgkmcnt(0)
	global_load_dwordx4 v[6:9], v[6:7], off offset:3072 nt
	s_addc_u32 s1, s21, s4
	v_lshl_add_u64 v[38:39], v[22:23], 1, s[0:1]
	v_lshl_add_u64 v[40:41], v[38:39], 0, s[14:15]
	v_add_co_u32_e32 v38, vcc, s18, v38
	global_load_dwordx2 v[42:43], v[40:41], off offset:512 nt
	global_load_dwordx2 v[44:45], v[40:41], off offset:1024 nt
	v_addc_co_u32_e32 v39, vcc, 0, v39, vcc
	global_load_dwordx2 v[38:39], v[38:39], off nt
	s_nop 0
	global_load_dwordx2 v[40:41], v[40:41], off offset:1536 nt
	v_lshl_add_u64 v[28:29], v[26:27], 0, s[2:3]
	s_add_i32 s16, s16, s17
	s_cmp_lt_i32 s16, 0x10000
	s_waitcnt vmcnt(7)
	v_pk_mul_f32 v[46:47], v[20:21], v[20:21]
	v_pk_mul_f32 v[48:49], v[18:19], v[18:19]
	s_waitcnt vmcnt(6)
	v_pk_mul_f32 v[50:51], v[16:17], v[16:17]
	v_pk_mul_f32 v[52:53], v[14:15], v[14:15]
	s_waitcnt vmcnt(5)
	v_pk_mul_f32 v[54:55], v[12:13], v[12:13]
	v_pk_mul_f32 v[56:57], v[10:11], v[10:11]
	v_pk_mov_b32 v[62:63], v[48:49], v[46:47] op_sel:[1,0]
	v_mov_b32_e32 v49, v47
	s_waitcnt vmcnt(4)
	v_pk_mul_f32 v[58:59], v[8:9], v[8:9]
	v_pk_mul_f32 v[60:61], v[6:7], v[6:7]
	v_pk_mov_b32 v[46:47], v[52:53], v[50:51] op_sel:[1,0]
	v_mov_b32_e32 v53, v51
	v_pk_mov_b32 v[50:51], v[56:57], v[54:55] op_sel:[1,0]
	v_mov_b32_e32 v57, v55
	v_pk_add_f32 v[48:49], v[62:63], v[48:49]
	v_pk_mov_b32 v[54:55], v[60:61], v[58:59] op_sel:[1,0]
	v_mov_b32_e32 v61, v59
	v_pk_add_f32 v[46:47], v[46:47], v[52:53]
	v_pk_add_f32 v[50:51], v[50:51], v[56:57]
	v_add_f32_e32 v37, v48, v49
	v_pk_add_f32 v[52:53], v[54:55], v[60:61]
	v_add_f32_e32 v54, v46, v47
	v_add_f32_e32 v55, v50, v51
	ds_bpermute_b32 v57, v1, v37
	s_waitcnt vmcnt(3)
	v_lshlrev_b32_e32 v46, 16, v42
	v_and_b32_e32 v47, 0xffff0000, v42
	v_lshlrev_b32_e32 v42, 16, v43
	v_and_b32_e32 v43, 0xffff0000, v43
	s_waitcnt vmcnt(2)
	v_lshlrev_b32_e32 v48, 16, v44
	v_and_b32_e32 v49, 0xffff0000, v44
	v_lshlrev_b32_e32 v44, 16, v45
	s_waitcnt vmcnt(1)
	v_lshlrev_b32_e32 v50, 16, v38
	v_and_b32_e32 v51, 0xffff0000, v38
	v_lshlrev_b32_e32 v38, 16, v39
	ds_bpermute_b32 v58, v1, v54
	ds_bpermute_b32 v63, v1, v55
	v_add_f32_e32 v56, v52, v53
	v_mul_f32_e32 v59, 0xbfb8aa3b, v46
	v_mul_f32_e32 v60, 0xbfb8aa3b, v47
	v_mul_f32_e32 v61, 0xbfb8aa3b, v42
	v_mul_f32_e32 v62, 0xbfb8aa3b, v43
	v_mul_f32_e32 v65, 0xbfb8aa3b, v49
	v_mul_f32_e32 v66, 0xbfb8aa3b, v44
	v_mul_f32_e32 v70, 0xbfb8aa3b, v51
	v_mul_f32_e32 v71, 0xbfb8aa3b, v38
	v_and_b32_e32 v45, 0xffff0000, v45
	v_and_b32_e32 v39, 0xffff0000, v39
	v_mul_f32_e32 v64, 0xbfb8aa3b, v48
	ds_bpermute_b32 v68, v1, v56
	v_exp_f32_e32 v59, v59
	v_exp_f32_e32 v60, v60
	v_exp_f32_e32 v61, v61
	v_exp_f32_e32 v62, v62
	v_exp_f32_e32 v65, v65
	v_exp_f32_e32 v66, v66
	v_exp_f32_e32 v70, v70
	v_exp_f32_e32 v71, v71
	v_mul_f32_e32 v67, 0xbfb8aa3b, v45
	v_mul_f32_e32 v72, 0xbfb8aa3b, v39
	v_exp_f32_e32 v64, v64
	v_exp_f32_e32 v67, v67
	v_exp_f32_e32 v72, v72
	s_waitcnt lgkmcnt(3)
	v_add_f32_e32 v37, v37, v57
	s_waitcnt lgkmcnt(2)
	v_add_f32_e32 v77, v54, v58
	s_waitcnt lgkmcnt(1)
	v_add_f32_e32 v78, v55, v63
	ds_bpermute_b32 v80, v30, v37
	v_add_f32_e32 v54, 1.0, v59
	v_add_f32_e32 v57, 1.0, v60
	v_add_f32_e32 v58, 1.0, v61
	v_add_f32_e32 v59, 1.0, v62
	v_add_f32_e32 v61, 1.0, v65
	v_add_f32_e32 v62, 1.0, v66
	v_add_f32_e32 v65, 1.0, v70
	v_add_f32_e32 v66, 1.0, v71
	ds_bpermute_b32 v70, v30, v77
	ds_bpermute_b32 v71, v30, v78
	v_add_f32_e32 v60, 1.0, v64
	s_waitcnt lgkmcnt(3)
	v_add_f32_e32 v79, v56, v68
	v_rcp_f32_e32 v54, v54
	v_rcp_f32_e32 v55, v57
	v_rcp_f32_e32 v56, v58
	v_rcp_f32_e32 v57, v59
	v_add_f32_e32 v63, 1.0, v67
	v_add_f32_e32 v67, 1.0, v72
	v_rcp_f32_e32 v58, v60
	v_rcp_f32_e32 v59, v61
	ds_bpermute_b32 v72, v30, v79
	v_rcp_f32_e32 v60, v62
	v_rcp_f32_e32 v61, v63
	s_waitcnt lgkmcnt(3)
	v_add_f32_e32 v37, v37, v80
	v_pk_mul_f32 v[46:47], v[54:55], v[46:47]
	v_pk_mul_f32 v[42:43], v[56:57], v[42:43]
	s_waitcnt lgkmcnt(2)
	v_add_f32_e32 v54, v77, v70
	s_waitcnt lgkmcnt(1)
	v_add_f32_e32 v55, v78, v71
	ds_bpermute_b32 v57, v31, v37
	v_pk_mul_f32 v[48:49], v[58:59], v[48:49]
	ds_bpermute_b32 v58, v31, v54
	ds_bpermute_b32 v59, v31, v55
	s_waitcnt lgkmcnt(3)
	v_add_f32_e32 v56, v79, v72
	v_pk_mul_f32 v[44:45], v[60:61], v[44:45]
	ds_bpermute_b32 v60, v31, v56
	s_waitcnt lgkmcnt(3)
	v_add_f32_e32 v37, v37, v57
	s_waitcnt lgkmcnt(2)
	v_add_f32_e32 v54, v54, v58
	s_waitcnt lgkmcnt(1)
	v_add_f32_e32 v55, v55, v59
	ds_bpermute_b32 v57, v32, v37
	ds_bpermute_b32 v58, v32, v54
	ds_bpermute_b32 v59, v32, v55
	s_waitcnt lgkmcnt(3)
	v_add_f32_e32 v56, v56, v60
	ds_bpermute_b32 v60, v32, v56
	s_waitcnt lgkmcnt(3)
	v_add_f32_e32 v37, v37, v57
	s_waitcnt lgkmcnt(2)
	v_add_f32_e32 v54, v54, v58
	s_waitcnt lgkmcnt(1)
	v_add_f32_e32 v55, v55, v59
	ds_bpermute_b32 v57, v33, v37
	ds_bpermute_b32 v58, v33, v54
	ds_bpermute_b32 v59, v33, v55
	s_waitcnt lgkmcnt(3)
	v_add_f32_e32 v56, v56, v60
	ds_bpermute_b32 v60, v33, v56
	s_waitcnt lgkmcnt(3)
	v_add_f32_e32 v37, v37, v57
	s_waitcnt lgkmcnt(2)
	v_add_f32_e32 v54, v54, v58
	s_waitcnt lgkmcnt(1)
	v_add_f32_e32 v55, v55, v59
	ds_bpermute_b32 v57, v34, v37
	ds_bpermute_b32 v58, v34, v54
	ds_bpermute_b32 v59, v34, v55
	s_waitcnt lgkmcnt(3)
	v_add_f32_e32 v56, v56, v60
	s_waitcnt vmcnt(0)
; DI unsigned pk2(float lo, float hi) { f32x2 v = {lo, hi}; bf16x2_t b = __builtin_convertvector(v, bf16x2_t); return __builtin_bit_cast(unsigned, b); }
; DI float siluf_(float x) { return x * sigmoidf_(x); }
; DI void gla_finalize_phase(Frame& F) {
;     ...
;         for (int h = 0; h < 4; ++h) {
;             const float ss = wave_sum((o[h][0] * o[h][0] + o[h][1] * o[h][1]) + (o[h][2] * o[h][2] + o[h][3] * o[h][3]));
;             const float rs = 1.f / sqrtf(ss * (1.f / 256.f) + LN_EPS);
;             u32x2 wv; wv.x = pk2(o[h][0] * rs * gn[0] * siluf_(gr[h][0]), o[h][1] * rs * gn[1] * siluf_(gr[h][1])); wv.y = pk2(o[h][2] * rs * gn[2] * siluf_(gr[h][2]), o[h][3] * rs * gn[3] * siluf_(gr[h][3]));
;             *(u32x2*)(F.MIX + (size_t)row * DM + h * 256 + 4 * lane) = wv; }
	v_lshlrev_b32_e32 v52, 16, v40
	v_and_b32_e32 v53, 0xffff0000, v40
	v_lshlrev_b32_e32 v40, 16, v41
	v_and_b32_e32 v41, 0xffff0000, v41
	ds_bpermute_b32 v60, v34, v56
	v_mul_f32_e32 v69, 0xbfb8aa3b, v50
	v_mul_f32_e32 v73, 0xbfb8aa3b, v52
	v_mul_f32_e32 v74, 0xbfb8aa3b, v53
	v_mul_f32_e32 v75, 0xbfb8aa3b, v40
	v_mul_f32_e32 v76, 0xbfb8aa3b, v41
	v_exp_f32_e32 v69, v69
	v_exp_f32_e32 v73, v73
	v_exp_f32_e32 v74, v74
	v_exp_f32_e32 v75, v75
	v_exp_f32_e32 v76, v76
	s_waitcnt lgkmcnt(3)
	v_add_f32_e32 v37, v37, v57
	s_waitcnt lgkmcnt(2)
	v_add_f32_e32 v54, v54, v58
	s_waitcnt lgkmcnt(1)
	v_add_f32_e32 v55, v55, v59
	v_fmamk_f32 v37, v37, 0x3b800000, v35
	v_fmamk_f32 v54, v54, 0x3b800000, v35
	v_fmamk_f32 v55, v55, 0x3b800000, v35
	v_mul_f32_e32 v57, 0x4f800000, v37
	v_cmp_gt_f32_e64 s[4:5], s19, v37
	s_waitcnt lgkmcnt(0)
	v_add_f32_e32 v56, v56, v60
	v_mul_f32_e32 v58, 0x4f800000, v54
	v_cmp_gt_f32_e32 vcc, s19, v54
	v_mul_f32_e32 v59, 0x4f800000, v55
	v_cmp_gt_f32_e64 s[0:1], s19, v55
	v_cndmask_b32_e64 v37, v37, v57, s[4:5]
	v_add_f32_e32 v64, 1.0, v69
	v_add_f32_e32 v68, 1.0, v73
	v_add_f32_e32 v69, 1.0, v74
	v_add_f32_e32 v73, 1.0, v75
	v_add_f32_e32 v74, 1.0, v76
	v_fmamk_f32 v56, v56, 0x3b800000, v35
	v_cndmask_b32_e32 v54, v54, v58, vcc
	v_cndmask_b32_e64 v55, v55, v59, s[0:1]
	v_sqrt_f32_e32 v57, v37
	v_rcp_f32_e32 v62, v64
	v_rcp_f32_e32 v63, v65
	v_rcp_f32_e32 v64, v66
	v_rcp_f32_e32 v65, v67
	v_rcp_f32_e32 v66, v68
	v_rcp_f32_e32 v67, v69
	v_rcp_f32_e32 v68, v73
	v_rcp_f32_e32 v69, v74
	v_mul_f32_e32 v60, 0x4f800000, v56
	v_cmp_gt_f32_e64 s[2:3], s19, v56
	v_sqrt_f32_e32 v58, v54
	v_sqrt_f32_e32 v59, v55
	v_cndmask_b32_e64 v56, v56, v60, s[2:3]
	v_sqrt_f32_e32 v60, v56
	v_add_u32_e32 v61, -1, v57
	v_pk_mul_f32 v[50:51], v[62:63], v[50:51]
	v_pk_mul_f32 v[38:39], v[64:65], v[38:39]
	v_pk_mul_f32 v[40:41], v[68:69], v[40:41]
	v_add_u32_e32 v62, 1, v57
	v_add_u32_e32 v63, -1, v58
	v_add_u32_e32 v65, -1, v59
	v_fma_f32 v69, -v61, v57, v37
	v_pk_mul_f32 v[52:53], v[66:67], v[52:53]
	v_add_u32_e32 v64, 1, v58
	v_add_u32_e32 v66, 1, v59
	v_fma_f32 v70, -v62, v57, v37
	v_fma_f32 v71, -v63, v58, v54
	v_fma_f32 v73, -v65, v59, v55
	v_cmp_ge_f32_e64 s[6:7], 0, v69
	v_add_u32_e32 v67, -1, v60
	v_fma_f32 v72, -v64, v58, v54
	v_fma_f32 v74, -v66, v59, v55
	v_cndmask_b32_e64 v57, v57, v61, s[6:7]
	v_cmp_ge_f32_e64 s[6:7], 0, v71
	v_cmp_ge_f32_e64 s[8:9], 0, v73
	v_cmp_lt_f32_e64 s[12:13], 0, v70
	v_add_u32_e32 v68, 1, v60
	v_fma_f32 v75, -v67, v60, v56
	v_cndmask_b32_e64 v58, v58, v63, s[6:7]
	v_cmp_lt_f32_e64 s[6:7], 0, v72
	v_cndmask_b32_e64 v59, v59, v65, s[8:9]
	v_cmp_lt_f32_e64 s[8:9], 0, v74
	v_cndmask_b32_e64 v57, v57, v62, s[12:13]
	v_fma_f32 v76, -v68, v60, v56
	v_cmp_ge_f32_e64 s[10:11], 0, v75
	v_cndmask_b32_e64 v58, v58, v64, s[6:7]
	v_cndmask_b32_e64 v59, v59, v66, s[8:9]
	v_mul_f32_e32 v61, 0x37800000, v57
	v_cndmask_b32_e64 v60, v60, v67, s[10:11]
	v_cmp_lt_f32_e64 s[10:11], 0, v76
	v_mul_f32_e32 v62, 0x37800000, v58
	v_mul_f32_e32 v63, 0x37800000, v59
	v_cndmask_b32_e64 v57, v57, v61, s[4:5]
	v_cmp_class_f32_e64 s[4:5], v37, v36
	v_cndmask_b32_e64 v60, v60, v68, s[10:11]
	v_cndmask_b32_e32 v58, v58, v62, vcc
	v_cmp_class_f32_e32 vcc, v54, v36
	v_cndmask_b32_e64 v59, v59, v63, s[0:1]
	v_cmp_class_f32_e64 s[0:1], v55, v36
	v_cndmask_b32_e64 v37, v57, v37, s[4:5]
	v_mul_f32_e32 v64, 0x37800000, v60
	v_cndmask_b32_e32 v57, v58, v54, vcc
	v_cndmask_b32_e64 v55, v59, v55, s[0:1]
	v_div_scale_f32 v54, s[0:1], v37, v37, 1.0
	v_cndmask_b32_e64 v60, v60, v64, s[2:3]
	v_cmp_class_f32_e64 s[2:3], v56, v36
	v_div_scale_f32 v59, s[0:1], v57, v57, 1.0
	v_rcp_f32_e32 v65, v54
	v_cndmask_b32_e64 v56, v60, v56, s[2:3]
	v_div_scale_f32 v61, s[2:3], v55, v55, 1.0
	v_rcp_f32_e32 v66, v59
	v_div_scale_f32 v63, s[4:5], v56, v56, 1.0
	v_rcp_f32_e32 v67, v61
	v_rcp_f32_e32 v68, v63
	v_fma_f32 v69, -v54, v65, 1.0
	v_div_scale_f32 v58, vcc, 1.0, v37, 1.0
	v_fma_f32 v70, -v59, v66, 1.0
	v_fmac_f32_e32 v65, v69, v65
	v_div_scale_f32 v60, s[0:1], 1.0, v57, 1.0
	v_fma_f32 v71, -v61, v67, 1.0
	v_fmac_f32_e32 v66, v70, v66
	v_mul_f32_e32 v69, v58, v65
	v_div_scale_f32 v62, s[2:3], 1.0, v55, 1.0
	v_fma_f32 v72, -v63, v68, 1.0
	v_fmac_f32_e32 v67, v71, v67
	v_mul_f32_e32 v70, v60, v66
	v_fma_f32 v73, -v54, v69, v58
	v_div_scale_f32 v64, s[4:5], 1.0, v56, 1.0
	v_fmac_f32_e32 v68, v72, v68
	v_mul_f32_e32 v71, v62, v67
	v_fma_f32 v74, -v59, v70, v60
	v_fmac_f32_e32 v69, v73, v65
	v_mul_f32_e32 v72, v64, v68
	v_fma_f32 v75, -v61, v71, v62
	v_fmac_f32_e32 v70, v74, v66
	v_fma_f32 v54, -v54, v69, v58
	v_fma_f32 v76, -v63, v72, v64
	v_fmac_f32_e32 v71, v75, v67
	v_fma_f32 v58, -v59, v70, v60
	v_div_fmas_f32 v54, v54, v65, v69
	s_mov_b64 vcc, s[0:1]
	v_fmac_f32_e32 v72, v76, v68
	v_fma_f32 v59, -v61, v71, v62
	v_div_fixup_f32 v54, v54, v37, 1.0
	v_div_fmas_f32 v37, v58, v66, v70
	s_mov_b64 vcc, s[2:3]
	v_fma_f32 v60, -v63, v72, v64
	v_pk_mul_f32 v[18:19], v[18:19], v[54:55] op_sel_hi:[1,0]
	v_pk_mul_f32 v[20:21], v[20:21], v[54:55] op_sel_hi:[1,0]
	v_div_fixup_f32 v54, v37, v57, 1.0
	v_div_fmas_f32 v37, v59, v67, v71
	s_mov_b64 vcc, s[4:5]
	v_pk_mul_f32 v[20:21], v[4:5], v[20:21]
	v_pk_mul_f32 v[14:15], v[14:15], v[54:55] op_sel_hi:[1,0]
	v_pk_mul_f32 v[16:17], v[16:17], v[54:55] op_sel_hi:[1,0]
	v_div_fixup_f32 v54, v37, v55, 1.0
	v_div_fmas_f32 v37, v60, v68, v72
	v_pk_mul_f32 v[20:21], v[38:39], v[20:21]
	v_div_fixup_f32 v38, v37, v56, 1.0
	v_pk_mul_f32 v[10:11], v[10:11], v[54:55] op_sel_hi:[1,0]
	v_pk_mul_f32 v[12:13], v[12:13], v[54:55] op_sel_hi:[1,0]
	v_pk_mul_f32 v[6:7], v[6:7], v[38:39] op_sel_hi:[1,0]
	v_pk_mul_f32 v[8:9], v[8:9], v[38:39] op_sel_hi:[1,0]
	v_pk_mul_f32 v[18:19], v[2:3], v[18:19]
	v_pk_mul_f32 v[14:15], v[2:3], v[14:15]
	v_pk_mul_f32 v[16:17], v[4:5], v[16:17]
	v_pk_mul_f32 v[10:11], v[2:3], v[10:11]
	v_pk_mul_f32 v[12:13], v[4:5], v[12:13]
	v_pk_mul_f32 v[6:7], v[2:3], v[6:7]
	v_pk_mul_f32 v[8:9], v[4:5], v[8:9]
	v_pk_mul_f32 v[18:19], v[50:51], v[18:19]
	v_pk_mul_f32 v[14:15], v[46:47], v[14:15]
	v_pk_mul_f32 v[16:17], v[42:43], v[16:17]
	v_pk_mul_f32 v[10:11], v[48:49], v[10:11]
	v_pk_mul_f32 v[12:13], v[44:45], v[12:13]
	v_pk_mul_f32 v[6:7], v[52:53], v[6:7]
	v_pk_mul_f32 v[8:9], v[40:41], v[8:9]
	v_cvt_pk_bf16_f32 v18, v18, v19
	v_cvt_pk_bf16_f32 v19, v20, v21
	v_cvt_pk_bf16_f32 v14, v14, v15
	v_cvt_pk_bf16_f32 v15, v16, v17
	v_cvt_pk_bf16_f32 v10, v10, v11
	v_cvt_pk_bf16_f32 v11, v12, v13
	v_cvt_pk_bf16_f32 v6, v6, v7
	v_cvt_pk_bf16_f32 v7, v8, v9
	global_store_dwordx2 v[28:29], v[18:19], off
	global_store_dwordx2 v[28:29], v[14:15], off offset:512
	global_store_dwordx2 v[28:29], v[10:11], off offset:1024
	global_store_dwordx2 v[28:29], v[6:7], off offset:1536
	s_cbranch_scc1 .LBB0_1727
